# PL1 + PW1 with R0=24576
# baseline (speedup 1.0000x reference)
; __device__ void p0_xconv(const Args& a) {
;     f16* XH = (f16*)(a.ws + WS_XH); float* SS = (float*)(a.ws + WS_SS);
;     int tid_ = threadIdx.x; asm volatile("" : "+v"(tid_));
;     const int lane = tid_ & 63, wv = tid_ >> 6;
;     const int nwv = (int)gridDim.x * 8;
;     for (int row0 = (int)blockIdx.x * 8 + wv; row0 < MROWS; row0 += 4 * nwv) {
.Lws_x:
	v_writelane_b32 v255, s14, 10
	v_writelane_b32 v255, s15, 11
	v_writelane_b32 v255, s20, 12
	v_writelane_b32 v255, s21, 13
	v_writelane_b32 v255, s22, 14
	v_writelane_b32 v255, s23, 15
	v_mov_b32_e32 v1, v0
	s_mov_b32 s3, 0x6000
	v_ashrrev_i32_e32 v2, 6, v1
	v_lshl_add_u32 v78, s2, 2, v2
	v_add_u32_e32 v78, -4, v78
	v_cmp_gt_i32_e32 vcc, s3, v78
	s_and_saveexec_b64 s[20:21], vcc
	s_cbranch_execz .Lxc_111
	v_and_b32_e32 v1, 63, v1
	v_mov_b32_e32 v67, 0
	v_lshlrev_b32_e32 v66, 2, v1
	v_lshlrev_b32_e32 v2, 3, v1
	v_mov_b32_e32 v3, v67
	s_movk_i32 s36, 0x80
	v_lshl_add_u64 v[68:69], s[40:41], 0, v[2:3]
	v_lshl_add_u64 v[2:3], s[40:41], 0, v[66:67]
	s_mov_b64 s[4:5], 0x1f800000
	v_cmp_gt_u32_e32 vcc, 16, v1
	v_lshl_add_u64 v[70:71], v[2:3], 0, s[4:5]
	v_cmp_eq_u32_e64 s[4:5], 0, v1
	v_mbcnt_lo_u32_b32 v1, -1, 0
	v_mbcnt_hi_u32_b32 v2, -1, v1
	v_and_b32_e32 v1, 64, v2
	v_add_u32_e32 v3, 64, v1
	v_xor_b32_e32 v1, 1, v2
	v_cmp_lt_i32_e64 s[6:7], v1, v3
	v_xor_b32_e32 v4, 2, v2
	s_waitcnt lgkmcnt(0)
	s_lshl_b32 s9, s36, 3
	v_cndmask_b32_e64 v1, v2, v1, s[6:7]
	v_cmp_lt_i32_e64 s[6:7], v4, v3
	s_add_i32 s44, s9, s9
	v_lshlrev_b32_e32 v1, 2, v1
	v_cndmask_b32_e64 v4, v2, v4, s[6:7]
	v_lshlrev_b32_e32 v80, 2, v4
	v_xor_b32_e32 v4, 4, v2
	v_cmp_lt_i32_e64 s[6:7], v4, v3
	s_lshl_b32 s33, s36, 4
	s_mul_i32 s36, s36, 24
	v_cndmask_b32_e64 v4, v2, v4, s[6:7]
	v_lshlrev_b32_e32 v81, 2, v4
	v_xor_b32_e32 v4, 8, v2
	v_cmp_lt_i32_e64 s[6:7], v4, v3
	s_mov_b64 s[22:23], 0
	s_movk_i32 s37, 0x4000
	v_cndmask_b32_e64 v4, v2, v4, s[6:7]
	v_lshlrev_b32_e32 v82, 2, v4
	v_xor_b32_e32 v4, 16, v2
	v_cmp_lt_i32_e64 s[6:7], v4, v3
	v_mov_b32_e32 v85, s19
	v_mov_b32_e32 v86, s17
	v_cndmask_b32_e64 v4, v2, v4, s[6:7]
	v_lshlrev_b32_e32 v83, 2, v4
	v_xor_b32_e32 v4, 32, v2
	v_cmp_lt_i32_e64 s[6:7], v4, v3
	v_mov_b32_e32 v87, s18
	v_mov_b32_e32 v88, s16
	v_cndmask_b32_e64 v2, v2, v4, s[6:7]
	v_lshlrev_b32_e32 v84, 2, v2
	v_lshlrev_b32_e32 v66, 2, v66
	s_add_i32 s44, s44, s9
	s_mov_b32 s45, 0x5fff
	s_branch .Lxc_94

; __device__ void p0_xconv(const Args& a) {
;     ...
;     for (int row0 = (int)blockIdx.x * 8 + wv; row0 < MROWS; row0 += 4 * nwv) {
;         f32x4 v[4][4];
; #pragma unroll
;         for (int r = 0; r < 4; ++r) {
;             const int row = row0 + r * nwv;
;             if (row < MROWS) {
;                 const float* src = (row < ROWS_PROMPT) ? a.x_prompt + (size_t)row * DM : a.x_sample + (size_t)(row - ROWS_PROMPT) * DM;
; #pragma unroll
;                 for (int i = 0; i < 4; ++i) v[r][i] = __builtin_nontemporal_load((const f32x4*)(src + i * 256 + lane * 4));
;             }
;         }
; #pragma unroll
;         for (int r = 0; r < 4; ++r) {
;             const int row = row0 + r * nwv;
;             if (row < MROWS) {
;                 float ss = 0.f;
; #pragma unroll
;                 for (int i = 0; i < 4; ++i) {
;                     const f32x4 x = v[r][i];
;                     ss += (x[0] * x[0] + x[1] * x[1]) + (x[2] * x[2] + x[3] * x[3]);
;                     f16x4 h; h[0] = (f16)x[0]; h[1] = (f16)x[1]; h[2] = (f16)x[2]; h[3] = (f16)x[3];
;                     *(f16x4*)(XH + (size_t)row * DM + i * 256 + lane * 4) = h;
.Lpw_x:
	s_barrier
	v_and_b32_e32 v136, 63, v0
	v_lshrrev_b32_e32 v137, 6, v0
	s_nop 0
	v_readfirstlane_b32 s3, v137
	s_nop 3
	s_lshl_b32 s4, s2, 2
	s_add_i32 s3, s3, s4
	s_add_i32 s3, s3, -4
	s_mov_b64 s[12:13], 1
	v_xor_b32_e32 v130, 1, v136
	v_lshlrev_b32_e32 v130, 2, v130
	v_xor_b32_e32 v131, 2, v136
	v_lshlrev_b32_e32 v131, 2, v131
	v_xor_b32_e32 v132, 4, v136
	v_lshlrev_b32_e32 v132, 2, v132
	v_xor_b32_e32 v133, 8, v136
	v_lshlrev_b32_e32 v133, 2, v133
	v_xor_b32_e32 v134, 16, v136
	v_lshlrev_b32_e32 v134, 2, v134
	v_xor_b32_e32 v135, 32, v136
	v_lshlrev_b32_e32 v135, 2, v135
	v_lshlrev_b32_e32 v140, 4, v136
	v_lshlrev_b32_e32 v144, 3, v136
	v_lshlrev_b32_e32 v186, 2, v136
	v_lshlrev_b32_e32 v141, 4, v136
	v_add_u32_e32 v141, 0x400000, v141
	v_lshlrev_b32_e32 v145, 3, v136
	v_add_u32_e32 v145, 0x200000, v145
	v_lshlrev_b32_e32 v187, 2, v136
	v_add_u32_e32 v187, 0x10000, v187
	v_lshlrev_b32_e32 v142, 4, v136
	v_add_u32_e32 v142, 0x800000, v142
	v_lshlrev_b32_e32 v146, 3, v136
	v_add_u32_e32 v146, 0x400000, v146
	v_lshlrev_b32_e32 v188, 2, v136
	v_add_u32_e32 v188, 0x20000, v188
	v_lshlrev_b32_e32 v143, 4, v136
	v_add_u32_e32 v143, 0xc00000, v143
	v_lshlrev_b32_e32 v147, 3, v136
	v_add_u32_e32 v147, 0x600000, v147
	v_lshlrev_b32_e32 v189, 2, v136
	v_add_u32_e32 v189, 0x30000, v189
	s_add_i32 s6, s3, 0x2000
	s_lshl_b32 s6, s6, 12
	s_add_u32 s4, s18, s6
	s_addc_u32 s5, s19, 0
	global_load_dwordx4 v[2:5], v140, s[4:5] nt
	global_load_dwordx4 v[6:9], v140, s[4:5] offset:1024 nt
	global_load_dwordx4 v[10:13], v140, s[4:5] offset:2048 nt
	global_load_dwordx4 v[14:17], v140, s[4:5] offset:3072 nt
	global_load_dwordx4 v[18:21], v141, s[4:5] nt
	global_load_dwordx4 v[22:25], v141, s[4:5] offset:1024 nt
	global_load_dwordx4 v[26:29], v141, s[4:5] offset:2048 nt
	global_load_dwordx4 v[30:33], v141, s[4:5] offset:3072 nt
	global_load_dwordx4 v[34:37], v142, s[4:5] nt
	global_load_dwordx4 v[38:41], v142, s[4:5] offset:1024 nt
	global_load_dwordx4 v[42:45], v142, s[4:5] offset:2048 nt
	global_load_dwordx4 v[46:49], v142, s[4:5] offset:3072 nt
	global_load_dwordx4 v[50:53], v143, s[4:5] nt
	global_load_dwordx4 v[54:57], v143, s[4:5] offset:1024 nt
	global_load_dwordx4 v[58:61], v143, s[4:5] offset:2048 nt
	global_load_dwordx4 v[62:65], v143, s[4:5] offset:3072 nt
	s_add_i32 s6, s3, 0x3000
	s_lshl_b32 s6, s6, 12
	s_add_u32 s4, s18, s6
	s_addc_u32 s5, s19, 0
	global_load_dwordx4 v[66:69], v140, s[4:5] nt
	global_load_dwordx4 v[70:73], v140, s[4:5] offset:1024 nt
	global_load_dwordx4 v[74:77], v140, s[4:5] offset:2048 nt
	global_load_dwordx4 v[78:81], v140, s[4:5] offset:3072 nt
	global_load_dwordx4 v[82:85], v141, s[4:5] nt
	global_load_dwordx4 v[86:89], v141, s[4:5] offset:1024 nt
	global_load_dwordx4 v[90:93], v141, s[4:5] offset:2048 nt
	global_load_dwordx4 v[94:97], v141, s[4:5] offset:3072 nt
	global_load_dwordx4 v[98:101], v142, s[4:5] nt
	global_load_dwordx4 v[102:105], v142, s[4:5] offset:1024 nt
	global_load_dwordx4 v[106:109], v142, s[4:5] offset:2048 nt
	global_load_dwordx4 v[110:113], v142, s[4:5] offset:3072 nt
	global_load_dwordx4 v[114:117], v143, s[4:5] nt
	global_load_dwordx4 v[118:121], v143, s[4:5] offset:1024 nt
	global_load_dwordx4 v[122:125], v143, s[4:5] offset:2048 nt
	global_load_dwordx4 v[126:129], v143, s[4:5] offset:3072 nt
	s_waitcnt vmcnt(16)
	s_add_i32 s6, s3, 0x6000
	s_lshl_b32 s7, s6, 11
	s_add_u32 s10, s40, s7
	s_addc_u32 s11, s41, 0
	s_lshl_b32 s7, s6, 6
	s_add_u32 s6, s40, s7
	s_addc_u32 s7, s41, 0
	s_add_u32 s6, s6, 0x1f800000
	s_addc_u32 s7, s7, 0
	v_mul_f32_e32 v150, v3, v3
	v_mul_f32_e32 v151, v5, v5
	v_fmac_f32_e32 v150, v2, v2
	v_fmac_f32_e32 v151, v4, v4
	v_add_f32_e32 v160, v150, v151
	v_cvt_pk_f16_f32 v170, v2, v3
	v_cvt_pk_f16_f32 v171, v4, v5
	v_mul_f32_e32 v150, v7, v7
	v_mul_f32_e32 v151, v9, v9
	v_fmac_f32_e32 v150, v6, v6
	v_fmac_f32_e32 v151, v8, v8
	v_add_f32_e32 v152, v150, v151
	v_add_f32_e32 v160, v160, v152
	v_cvt_pk_f16_f32 v172, v6, v7
	v_cvt_pk_f16_f32 v173, v8, v9
	v_mul_f32_e32 v150, v11, v11
	v_mul_f32_e32 v151, v13, v13
	v_fmac_f32_e32 v150, v10, v10
	v_fmac_f32_e32 v151, v12, v12
	v_add_f32_e32 v152, v150, v151
	v_add_f32_e32 v160, v160, v152
	v_cvt_pk_f16_f32 v174, v10, v11
	v_cvt_pk_f16_f32 v175, v12, v13
	v_mul_f32_e32 v150, v15, v15
	v_mul_f32_e32 v151, v17, v17
	v_fmac_f32_e32 v150, v14, v14
	v_fmac_f32_e32 v151, v16, v16
	v_add_f32_e32 v152, v150, v151
	v_add_f32_e32 v160, v160, v152
	v_cvt_pk_f16_f32 v176, v14, v15
	v_cvt_pk_f16_f32 v177, v16, v17
	global_store_dwordx2 v144, v[170:171], s[10:11]
	global_store_dwordx2 v144, v[172:173], s[10:11] offset:512
	global_store_dwordx2 v144, v[174:175], s[10:11] offset:1024
	global_store_dwordx2 v144, v[176:177], s[10:11] offset:1536
	v_mul_f32_e32 v150, v19, v19
	v_mul_f32_e32 v151, v21, v21
	v_fmac_f32_e32 v150, v18, v18
	v_fmac_f32_e32 v151, v20, v20
	v_add_f32_e32 v161, v150, v151
	v_cvt_pk_f16_f32 v178, v18, v19
	v_cvt_pk_f16_f32 v179, v20, v21
	v_mul_f32_e32 v150, v23, v23
	v_mul_f32_e32 v151, v25, v25
	v_fmac_f32_e32 v150, v22, v22
	v_fmac_f32_e32 v151, v24, v24
	v_add_f32_e32 v152, v150, v151
	v_add_f32_e32 v161, v161, v152
	v_cvt_pk_f16_f32 v180, v22, v23
	v_cvt_pk_f16_f32 v181, v24, v25
	v_mul_f32_e32 v150, v27, v27
	v_mul_f32_e32 v151, v29, v29
	v_fmac_f32_e32 v150, v26, v26
	v_fmac_f32_e32 v151, v28, v28
	v_add_f32_e32 v152, v150, v151
	v_add_f32_e32 v161, v161, v152
	v_cvt_pk_f16_f32 v182, v26, v27
	v_cvt_pk_f16_f32 v183, v28, v29
	v_mul_f32_e32 v150, v31, v31
	v_mul_f32_e32 v151, v33, v33
	v_fmac_f32_e32 v150, v30, v30
	v_fmac_f32_e32 v151, v32, v32
	v_add_f32_e32 v152, v150, v151
	v_add_f32_e32 v161, v161, v152
; __device__ void p0_xconv(const Args& a) {
;     ...
;                 float ss = 0.f;
; #pragma unroll
;                 for (int i = 0; i < 4; ++i) {
;                     const f32x4 x = v[r][i];
;                     ss += (x[0] * x[0] + x[1] * x[1]) + (x[2] * x[2] + x[3] * x[3]);
;                     f16x4 h; h[0] = (f16)x[0]; h[1] = (f16)x[1]; h[2] = (f16)x[2]; h[3] = (f16)x[3];
;                     *(f16x4*)(XH + (size_t)row * DM + i * 256 + lane * 4) = h;
;                 }
; #pragma unroll
;                 for (int o = 1; o < 64; o <<= 1) ss += __shfl_xor(ss, o);
;                 if (lane < 16) SS[(size_t)row * 16 + lane] = (lane == 0) ? ss : 0.f;
	v_cvt_pk_f16_f32 v184, v30, v31
	v_cvt_pk_f16_f32 v185, v32, v33
	global_store_dwordx2 v145, v[178:179], s[10:11]
	global_store_dwordx2 v145, v[180:181], s[10:11] offset:512
	global_store_dwordx2 v145, v[182:183], s[10:11] offset:1024
	global_store_dwordx2 v145, v[184:185], s[10:11] offset:1536
	v_mul_f32_e32 v150, v35, v35
	v_mul_f32_e32 v151, v37, v37
	v_fmac_f32_e32 v150, v34, v34
	v_fmac_f32_e32 v151, v36, v36
	v_add_f32_e32 v162, v150, v151
	v_cvt_pk_f16_f32 v170, v34, v35
	v_cvt_pk_f16_f32 v171, v36, v37
	v_mul_f32_e32 v150, v39, v39
	v_mul_f32_e32 v151, v41, v41
	v_fmac_f32_e32 v150, v38, v38
	v_fmac_f32_e32 v151, v40, v40
	v_add_f32_e32 v152, v150, v151
	v_add_f32_e32 v162, v162, v152
	v_cvt_pk_f16_f32 v172, v38, v39
	v_cvt_pk_f16_f32 v173, v40, v41
	v_mul_f32_e32 v150, v43, v43
	v_mul_f32_e32 v151, v45, v45
	v_fmac_f32_e32 v150, v42, v42
	v_fmac_f32_e32 v151, v44, v44
	v_add_f32_e32 v152, v150, v151
	v_add_f32_e32 v162, v162, v152
	v_cvt_pk_f16_f32 v174, v42, v43
	v_cvt_pk_f16_f32 v175, v44, v45
	v_mul_f32_e32 v150, v47, v47
	v_mul_f32_e32 v151, v49, v49
	v_fmac_f32_e32 v150, v46, v46
	v_fmac_f32_e32 v151, v48, v48
	v_add_f32_e32 v152, v150, v151
	v_add_f32_e32 v162, v162, v152
	v_cvt_pk_f16_f32 v176, v46, v47
	v_cvt_pk_f16_f32 v177, v48, v49
	global_store_dwordx2 v146, v[170:171], s[10:11]
	global_store_dwordx2 v146, v[172:173], s[10:11] offset:512
	global_store_dwordx2 v146, v[174:175], s[10:11] offset:1024
	global_store_dwordx2 v146, v[176:177], s[10:11] offset:1536
	v_mul_f32_e32 v150, v51, v51
	v_mul_f32_e32 v151, v53, v53
	v_fmac_f32_e32 v150, v50, v50
	v_fmac_f32_e32 v151, v52, v52
	v_add_f32_e32 v163, v150, v151
	v_cvt_pk_f16_f32 v178, v50, v51
	v_cvt_pk_f16_f32 v179, v52, v53
	v_mul_f32_e32 v150, v55, v55
	v_mul_f32_e32 v151, v57, v57
	v_fmac_f32_e32 v150, v54, v54
	v_fmac_f32_e32 v151, v56, v56
	v_add_f32_e32 v152, v150, v151
	v_add_f32_e32 v163, v163, v152
	v_cvt_pk_f16_f32 v180, v54, v55
	v_cvt_pk_f16_f32 v181, v56, v57
	v_mul_f32_e32 v150, v59, v59
	v_mul_f32_e32 v151, v61, v61
	v_fmac_f32_e32 v150, v58, v58
	v_fmac_f32_e32 v151, v60, v60
	v_add_f32_e32 v152, v150, v151
	v_add_f32_e32 v163, v163, v152
	v_cvt_pk_f16_f32 v182, v58, v59
	v_cvt_pk_f16_f32 v183, v60, v61
	v_mul_f32_e32 v150, v63, v63
	v_mul_f32_e32 v151, v65, v65
	v_fmac_f32_e32 v150, v62, v62
	v_fmac_f32_e32 v151, v64, v64
	v_add_f32_e32 v152, v150, v151
	v_add_f32_e32 v163, v163, v152
	v_cvt_pk_f16_f32 v184, v62, v63
	v_cvt_pk_f16_f32 v185, v64, v65
	global_store_dwordx2 v147, v[178:179], s[10:11]
	global_store_dwordx2 v147, v[180:181], s[10:11] offset:512
	global_store_dwordx2 v147, v[182:183], s[10:11] offset:1024
	global_store_dwordx2 v147, v[184:185], s[10:11] offset:1536
	ds_bpermute_b32 v164, v130, v160
	ds_bpermute_b32 v165, v130, v161
	ds_bpermute_b32 v166, v130, v162
	ds_bpermute_b32 v167, v130, v163
	s_waitcnt lgkmcnt(0)
	v_add_f32_e32 v160, v160, v164
	v_add_f32_e32 v161, v161, v165
	v_add_f32_e32 v162, v162, v166
	v_add_f32_e32 v163, v163, v167
	ds_bpermute_b32 v164, v131, v160
	ds_bpermute_b32 v165, v131, v161
	ds_bpermute_b32 v166, v131, v162
	ds_bpermute_b32 v167, v131, v163
	s_waitcnt lgkmcnt(0)
	v_add_f32_e32 v160, v160, v164
	v_add_f32_e32 v161, v161, v165
	v_add_f32_e32 v162, v162, v166
	v_add_f32_e32 v163, v163, v167
	ds_bpermute_b32 v164, v132, v160
	ds_bpermute_b32 v165, v132, v161
	ds_bpermute_b32 v166, v132, v162
	ds_bpermute_b32 v167, v132, v163
	s_waitcnt lgkmcnt(0)
	v_add_f32_e32 v160, v160, v164
	v_add_f32_e32 v161, v161, v165
	v_add_f32_e32 v162, v162, v166
	v_add_f32_e32 v163, v163, v167
	ds_bpermute_b32 v164, v133, v160
	ds_bpermute_b32 v165, v133, v161
	ds_bpermute_b32 v166, v133, v162
	ds_bpermute_b32 v167, v133, v163
	s_waitcnt lgkmcnt(0)
	v_add_f32_e32 v160, v160, v164
	v_add_f32_e32 v161, v161, v165
	v_add_f32_e32 v162, v162, v166
	v_add_f32_e32 v163, v163, v167
	ds_bpermute_b32 v164, v134, v160
	ds_bpermute_b32 v165, v134, v161
	ds_bpermute_b32 v166, v134, v162
	ds_bpermute_b32 v167, v134, v163
	s_waitcnt lgkmcnt(0)
	v_add_f32_e32 v160, v160, v164
	v_add_f32_e32 v161, v161, v165
	v_add_f32_e32 v162, v162, v166
	v_add_f32_e32 v163, v163, v167
	ds_bpermute_b32 v164, v135, v160
	ds_bpermute_b32 v165, v135, v161
	ds_bpermute_b32 v166, v135, v162
	ds_bpermute_b32 v167, v135, v163
	s_waitcnt lgkmcnt(0)
	v_add_f32_e32 v160, v160, v164
	v_add_f32_e32 v161, v161, v165
	v_add_f32_e32 v162, v162, v166
	v_add_f32_e32 v163, v163, v167
	v_cndmask_b32_e64 v164, 0, v160, s[12:13]
	v_cndmask_b32_e64 v165, 0, v161, s[12:13]
	v_cndmask_b32_e64 v166, 0, v162, s[12:13]
	v_cndmask_b32_e64 v167, 0, v163, s[12:13]
	s_mov_b64 exec, 0xffff
	global_store_dword v186, v164, s[6:7]
	global_store_dword v187, v165, s[6:7]
	global_store_dword v188, v166, s[6:7]
	global_store_dword v189, v167, s[6:7]
	s_mov_b64 exec, -1
	s_barrier
; __device__ void p0_xconv(const Args& a) {
;     ...
;     for (int row0 = (int)blockIdx.x * 8 + wv; row0 < MROWS; row0 += 4 * nwv) {
;         f32x4 v[4][4];
; #pragma unroll
;         for (int r = 0; r < 4; ++r) {
;             const int row = row0 + r * nwv;
;             if (row < MROWS) {
;                 const float* src = (row < ROWS_PROMPT) ? a.x_prompt + (size_t)row * DM : a.x_sample + (size_t)(row - ROWS_PROMPT) * DM;
; #pragma unroll
;                 for (int i = 0; i < 4; ++i) v[r][i] = __builtin_nontemporal_load((const f32x4*)(src + i * 256 + lane * 4));
;             }
;         }
; #pragma unroll
;         for (int r = 0; r < 4; ++r) {
;             const int row = row0 + r * nwv;
;             if (row < MROWS) {
;                 float ss = 0.f;
; #pragma unroll
;                 for (int i = 0; i < 4; ++i) {
;                     const f32x4 x = v[r][i];
;                     ss += (x[0] * x[0] + x[1] * x[1]) + (x[2] * x[2] + x[3] * x[3]);
;                     f16x4 h; h[0] = (f16)x[0]; h[1] = (f16)x[1]; h[2] = (f16)x[2]; h[3] = (f16)x[3];
;                     *(f16x4*)(XH + (size_t)row * DM + i * 256 + lane * 4) = h;
	s_add_i32 s6, s3, 0x4000
	s_lshl_b32 s6, s6, 12
	s_add_u32 s4, s18, s6
	s_addc_u32 s5, s19, 0
	global_load_dwordx4 v[2:5], v140, s[4:5] nt
	global_load_dwordx4 v[6:9], v140, s[4:5] offset:1024 nt
	global_load_dwordx4 v[10:13], v140, s[4:5] offset:2048 nt
	global_load_dwordx4 v[14:17], v140, s[4:5] offset:3072 nt
	global_load_dwordx4 v[18:21], v141, s[4:5] nt
	global_load_dwordx4 v[22:25], v141, s[4:5] offset:1024 nt
	global_load_dwordx4 v[26:29], v141, s[4:5] offset:2048 nt
	global_load_dwordx4 v[30:33], v141, s[4:5] offset:3072 nt
	global_load_dwordx4 v[34:37], v142, s[4:5] nt
	global_load_dwordx4 v[38:41], v142, s[4:5] offset:1024 nt
	global_load_dwordx4 v[42:45], v142, s[4:5] offset:2048 nt
	global_load_dwordx4 v[46:49], v142, s[4:5] offset:3072 nt
	global_load_dwordx4 v[50:53], v143, s[4:5] nt
	global_load_dwordx4 v[54:57], v143, s[4:5] offset:1024 nt
	global_load_dwordx4 v[58:61], v143, s[4:5] offset:2048 nt
	global_load_dwordx4 v[62:65], v143, s[4:5] offset:3072 nt
	s_waitcnt vmcnt(36)
	s_add_i32 s6, s3, 0x7000
	s_lshl_b32 s7, s6, 11
	s_add_u32 s10, s40, s7
	s_addc_u32 s11, s41, 0
	s_lshl_b32 s7, s6, 6
	s_add_u32 s6, s40, s7
	s_addc_u32 s7, s41, 0
	s_add_u32 s6, s6, 0x1f800000
	s_addc_u32 s7, s7, 0
	v_mul_f32_e32 v150, v67, v67
	v_mul_f32_e32 v151, v69, v69
	v_fmac_f32_e32 v150, v66, v66
	v_fmac_f32_e32 v151, v68, v68
	v_add_f32_e32 v160, v150, v151
	v_cvt_pk_f16_f32 v170, v66, v67
	v_cvt_pk_f16_f32 v171, v68, v69
	v_mul_f32_e32 v150, v71, v71
	v_mul_f32_e32 v151, v73, v73
	v_fmac_f32_e32 v150, v70, v70
	v_fmac_f32_e32 v151, v72, v72
	v_add_f32_e32 v152, v150, v151
	v_add_f32_e32 v160, v160, v152
	v_cvt_pk_f16_f32 v172, v70, v71
	v_cvt_pk_f16_f32 v173, v72, v73
	v_mul_f32_e32 v150, v75, v75
	v_mul_f32_e32 v151, v77, v77
	v_fmac_f32_e32 v150, v74, v74
	v_fmac_f32_e32 v151, v76, v76
	v_add_f32_e32 v152, v150, v151
	v_add_f32_e32 v160, v160, v152
	v_cvt_pk_f16_f32 v174, v74, v75
	v_cvt_pk_f16_f32 v175, v76, v77
	v_mul_f32_e32 v150, v79, v79
	v_mul_f32_e32 v151, v81, v81
	v_fmac_f32_e32 v150, v78, v78
	v_fmac_f32_e32 v151, v80, v80
	v_add_f32_e32 v152, v150, v151
	v_add_f32_e32 v160, v160, v152
	v_cvt_pk_f16_f32 v176, v78, v79
	v_cvt_pk_f16_f32 v177, v80, v81
	global_store_dwordx2 v144, v[170:171], s[10:11]
	global_store_dwordx2 v144, v[172:173], s[10:11] offset:512
	global_store_dwordx2 v144, v[174:175], s[10:11] offset:1024
	global_store_dwordx2 v144, v[176:177], s[10:11] offset:1536
	v_mul_f32_e32 v150, v83, v83
	v_mul_f32_e32 v151, v85, v85
	v_fmac_f32_e32 v150, v82, v82
	v_fmac_f32_e32 v151, v84, v84
	v_add_f32_e32 v161, v150, v151
	v_cvt_pk_f16_f32 v178, v82, v83
	v_cvt_pk_f16_f32 v179, v84, v85
	v_mul_f32_e32 v150, v87, v87
	v_mul_f32_e32 v151, v89, v89
	v_fmac_f32_e32 v150, v86, v86
	v_fmac_f32_e32 v151, v88, v88
	v_add_f32_e32 v152, v150, v151
	v_add_f32_e32 v161, v161, v152
	v_cvt_pk_f16_f32 v180, v86, v87
	v_cvt_pk_f16_f32 v181, v88, v89
	v_mul_f32_e32 v150, v91, v91
	v_mul_f32_e32 v151, v93, v93
	v_fmac_f32_e32 v150, v90, v90
	v_fmac_f32_e32 v151, v92, v92
	v_add_f32_e32 v152, v150, v151
	v_add_f32_e32 v161, v161, v152
	v_cvt_pk_f16_f32 v182, v90, v91
	v_cvt_pk_f16_f32 v183, v92, v93
	v_mul_f32_e32 v150, v95, v95
	v_mul_f32_e32 v151, v97, v97
	v_fmac_f32_e32 v150, v94, v94
	v_fmac_f32_e32 v151, v96, v96
	v_add_f32_e32 v152, v150, v151
	v_add_f32_e32 v161, v161, v152
	v_cvt_pk_f16_f32 v184, v94, v95
	v_cvt_pk_f16_f32 v185, v96, v97
	global_store_dwordx2 v145, v[178:179], s[10:11]
	global_store_dwordx2 v145, v[180:181], s[10:11] offset:512
	global_store_dwordx2 v145, v[182:183], s[10:11] offset:1024
	global_store_dwordx2 v145, v[184:185], s[10:11] offset:1536
	v_mul_f32_e32 v150, v99, v99
	v_mul_f32_e32 v151, v101, v101
	v_fmac_f32_e32 v150, v98, v98
	v_fmac_f32_e32 v151, v100, v100
	v_add_f32_e32 v162, v150, v151
	v_cvt_pk_f16_f32 v170, v98, v99
	v_cvt_pk_f16_f32 v171, v100, v101
	v_mul_f32_e32 v150, v103, v103
	v_mul_f32_e32 v151, v105, v105
	v_fmac_f32_e32 v150, v102, v102
	v_fmac_f32_e32 v151, v104, v104
	v_add_f32_e32 v152, v150, v151
	v_add_f32_e32 v162, v162, v152
	v_cvt_pk_f16_f32 v172, v102, v103
	v_cvt_pk_f16_f32 v173, v104, v105
	v_mul_f32_e32 v150, v107, v107
	v_mul_f32_e32 v151, v109, v109
	v_fmac_f32_e32 v150, v106, v106
	v_fmac_f32_e32 v151, v108, v108
	v_add_f32_e32 v152, v150, v151
	v_add_f32_e32 v162, v162, v152
	v_cvt_pk_f16_f32 v174, v106, v107
	v_cvt_pk_f16_f32 v175, v108, v109
	v_mul_f32_e32 v150, v111, v111
	v_mul_f32_e32 v151, v113, v113
	v_fmac_f32_e32 v150, v110, v110
	v_fmac_f32_e32 v151, v112, v112
	v_add_f32_e32 v152, v150, v151
	v_add_f32_e32 v162, v162, v152
	v_cvt_pk_f16_f32 v176, v110, v111
	v_cvt_pk_f16_f32 v177, v112, v113
	global_store_dwordx2 v146, v[170:171], s[10:11]
	global_store_dwordx2 v146, v[172:173], s[10:11] offset:512
	global_store_dwordx2 v146, v[174:175], s[10:11] offset:1024
	global_store_dwordx2 v146, v[176:177], s[10:11] offset:1536
	v_mul_f32_e32 v150, v115, v115
	v_mul_f32_e32 v151, v117, v117
	v_fmac_f32_e32 v150, v114, v114
	v_fmac_f32_e32 v151, v116, v116
	v_add_f32_e32 v163, v150, v151
	v_cvt_pk_f16_f32 v178, v114, v115
	v_cvt_pk_f16_f32 v179, v116, v117
	v_mul_f32_e32 v150, v119, v119
	v_mul_f32_e32 v151, v121, v121
	v_fmac_f32_e32 v150, v118, v118
	v_fmac_f32_e32 v151, v120, v120
	v_add_f32_e32 v152, v150, v151
	v_add_f32_e32 v163, v163, v152
	v_cvt_pk_f16_f32 v180, v118, v119
	v_cvt_pk_f16_f32 v181, v120, v121
	v_mul_f32_e32 v150, v123, v123
	v_mul_f32_e32 v151, v125, v125
	v_fmac_f32_e32 v150, v122, v122
	v_fmac_f32_e32 v151, v124, v124
	v_add_f32_e32 v152, v150, v151
	v_add_f32_e32 v163, v163, v152
	v_cvt_pk_f16_f32 v182, v122, v123
	v_cvt_pk_f16_f32 v183, v124, v125
	v_mul_f32_e32 v150, v127, v127
	v_mul_f32_e32 v151, v129, v129
	v_fmac_f32_e32 v150, v126, v126
	v_fmac_f32_e32 v151, v128, v128
	v_add_f32_e32 v152, v150, v151
	v_add_f32_e32 v163, v163, v152
	v_cvt_pk_f16_f32 v184, v126, v127
	v_cvt_pk_f16_f32 v185, v128, v129
	global_store_dwordx2 v147, v[178:179], s[10:11]
	global_store_dwordx2 v147, v[180:181], s[10:11] offset:512
	global_store_dwordx2 v147, v[182:183], s[10:11] offset:1024
	global_store_dwordx2 v147, v[184:185], s[10:11] offset:1536
	ds_bpermute_b32 v164, v130, v160
	ds_bpermute_b32 v165, v130, v161
	ds_bpermute_b32 v166, v130, v162
	ds_bpermute_b32 v167, v130, v163
	s_waitcnt lgkmcnt(0)
; __device__ void p0_xconv(const Args& a) {
;     ...
;         for (int r = 0; r < 4; ++r) {
;             const int row = row0 + r * nwv;
;             if (row < MROWS) {
;                 float ss = 0.f;
; #pragma unroll
;                 for (int i = 0; i < 4; ++i) {
;                     const f32x4 x = v[r][i];
;                     ss += (x[0] * x[0] + x[1] * x[1]) + (x[2] * x[2] + x[3] * x[3]);
;                     f16x4 h; h[0] = (f16)x[0]; h[1] = (f16)x[1]; h[2] = (f16)x[2]; h[3] = (f16)x[3];
;                     *(f16x4*)(XH + (size_t)row * DM + i * 256 + lane * 4) = h;
;                 }
; #pragma unroll
;                 for (int o = 1; o < 64; o <<= 1) ss += __shfl_xor(ss, o);
;                 if (lane < 16) SS[(size_t)row * 16 + lane] = (lane == 0) ? ss : 0.f;
	v_add_f32_e32 v160, v160, v164
	v_add_f32_e32 v161, v161, v165
	v_add_f32_e32 v162, v162, v166
	v_add_f32_e32 v163, v163, v167
	ds_bpermute_b32 v164, v131, v160
	ds_bpermute_b32 v165, v131, v161
	ds_bpermute_b32 v166, v131, v162
	ds_bpermute_b32 v167, v131, v163
	s_waitcnt lgkmcnt(0)
	v_add_f32_e32 v160, v160, v164
	v_add_f32_e32 v161, v161, v165
	v_add_f32_e32 v162, v162, v166
	v_add_f32_e32 v163, v163, v167
	ds_bpermute_b32 v164, v132, v160
	ds_bpermute_b32 v165, v132, v161
	ds_bpermute_b32 v166, v132, v162
	ds_bpermute_b32 v167, v132, v163
	s_waitcnt lgkmcnt(0)
	v_add_f32_e32 v160, v160, v164
	v_add_f32_e32 v161, v161, v165
	v_add_f32_e32 v162, v162, v166
	v_add_f32_e32 v163, v163, v167
	ds_bpermute_b32 v164, v133, v160
	ds_bpermute_b32 v165, v133, v161
	ds_bpermute_b32 v166, v133, v162
	ds_bpermute_b32 v167, v133, v163
	s_waitcnt lgkmcnt(0)
	v_add_f32_e32 v160, v160, v164
	v_add_f32_e32 v161, v161, v165
	v_add_f32_e32 v162, v162, v166
	v_add_f32_e32 v163, v163, v167
	ds_bpermute_b32 v164, v134, v160
	ds_bpermute_b32 v165, v134, v161
	ds_bpermute_b32 v166, v134, v162
	ds_bpermute_b32 v167, v134, v163
	s_waitcnt lgkmcnt(0)
	v_add_f32_e32 v160, v160, v164
	v_add_f32_e32 v161, v161, v165
	v_add_f32_e32 v162, v162, v166
	v_add_f32_e32 v163, v163, v167
	ds_bpermute_b32 v164, v135, v160
	ds_bpermute_b32 v165, v135, v161
	ds_bpermute_b32 v166, v135, v162
	ds_bpermute_b32 v167, v135, v163
	s_waitcnt lgkmcnt(0)
	v_add_f32_e32 v160, v160, v164
	v_add_f32_e32 v161, v161, v165
	v_add_f32_e32 v162, v162, v166
	v_add_f32_e32 v163, v163, v167
	v_cndmask_b32_e64 v164, 0, v160, s[12:13]
	v_cndmask_b32_e64 v165, 0, v161, s[12:13]
	v_cndmask_b32_e64 v166, 0, v162, s[12:13]
	v_cndmask_b32_e64 v167, 0, v163, s[12:13]
	s_mov_b64 exec, 0xffff
	global_store_dword v186, v164, s[6:7]
	global_store_dword v187, v165, s[6:7]
	global_store_dword v188, v166, s[6:7]
	global_store_dword v189, v167, s[6:7]
	s_mov_b64 exec, -1
	s_add_i32 s6, s3, 0x5000
	s_lshl_b32 s6, s6, 12
	s_add_u32 s4, s18, s6
	s_addc_u32 s5, s19, 0
	global_load_dwordx4 v[66:69], v140, s[4:5] nt
	global_load_dwordx4 v[70:73], v140, s[4:5] offset:1024 nt
	global_load_dwordx4 v[74:77], v140, s[4:5] offset:2048 nt
	global_load_dwordx4 v[78:81], v140, s[4:5] offset:3072 nt
	global_load_dwordx4 v[82:85], v141, s[4:5] nt
	global_load_dwordx4 v[86:89], v141, s[4:5] offset:1024 nt
	global_load_dwordx4 v[90:93], v141, s[4:5] offset:2048 nt
	global_load_dwordx4 v[94:97], v141, s[4:5] offset:3072 nt
	global_load_dwordx4 v[98:101], v142, s[4:5] nt
	global_load_dwordx4 v[102:105], v142, s[4:5] offset:1024 nt
	global_load_dwordx4 v[106:109], v142, s[4:5] offset:2048 nt
	global_load_dwordx4 v[110:113], v142, s[4:5] offset:3072 nt
	global_load_dwordx4 v[114:117], v143, s[4:5] nt
	global_load_dwordx4 v[118:121], v143, s[4:5] offset:1024 nt
	global_load_dwordx4 v[122:125], v143, s[4:5] offset:2048 nt
	global_load_dwordx4 v[126:129], v143, s[4:5] offset:3072 nt
	s_waitcnt vmcnt(36)
	s_add_i32 s6, s3, 0x8000
	s_lshl_b32 s7, s6, 11
	s_add_u32 s10, s40, s7
	s_addc_u32 s11, s41, 0
	s_lshl_b32 s7, s6, 6
	s_add_u32 s6, s40, s7
	s_addc_u32 s7, s41, 0
	s_add_u32 s6, s6, 0x1f800000
	s_addc_u32 s7, s7, 0
	v_mul_f32_e32 v150, v3, v3
	v_mul_f32_e32 v151, v5, v5
	v_fmac_f32_e32 v150, v2, v2
	v_fmac_f32_e32 v151, v4, v4
	v_add_f32_e32 v160, v150, v151
	v_cvt_pk_f16_f32 v170, v2, v3
	v_cvt_pk_f16_f32 v171, v4, v5
	v_mul_f32_e32 v150, v7, v7
	v_mul_f32_e32 v151, v9, v9
	v_fmac_f32_e32 v150, v6, v6
	v_fmac_f32_e32 v151, v8, v8
	v_add_f32_e32 v152, v150, v151
	v_add_f32_e32 v160, v160, v152
	v_cvt_pk_f16_f32 v172, v6, v7
	v_cvt_pk_f16_f32 v173, v8, v9
	v_mul_f32_e32 v150, v11, v11
	v_mul_f32_e32 v151, v13, v13
	v_fmac_f32_e32 v150, v10, v10
	v_fmac_f32_e32 v151, v12, v12
	v_add_f32_e32 v152, v150, v151
	v_add_f32_e32 v160, v160, v152
	v_cvt_pk_f16_f32 v174, v10, v11
	v_cvt_pk_f16_f32 v175, v12, v13
	v_mul_f32_e32 v150, v15, v15
	v_mul_f32_e32 v151, v17, v17
	v_fmac_f32_e32 v150, v14, v14
	v_fmac_f32_e32 v151, v16, v16
	v_add_f32_e32 v152, v150, v151
	v_add_f32_e32 v160, v160, v152
	v_cvt_pk_f16_f32 v176, v14, v15
	v_cvt_pk_f16_f32 v177, v16, v17
	global_store_dwordx2 v144, v[170:171], s[10:11]
	global_store_dwordx2 v144, v[172:173], s[10:11] offset:512
	global_store_dwordx2 v144, v[174:175], s[10:11] offset:1024
	global_store_dwordx2 v144, v[176:177], s[10:11] offset:1536
	v_mul_f32_e32 v150, v19, v19
	v_mul_f32_e32 v151, v21, v21
	v_fmac_f32_e32 v150, v18, v18
	v_fmac_f32_e32 v151, v20, v20
	v_add_f32_e32 v161, v150, v151
	v_cvt_pk_f16_f32 v178, v18, v19
	v_cvt_pk_f16_f32 v179, v20, v21
	v_mul_f32_e32 v150, v23, v23
	v_mul_f32_e32 v151, v25, v25
	v_fmac_f32_e32 v150, v22, v22
	v_fmac_f32_e32 v151, v24, v24
	v_add_f32_e32 v152, v150, v151
	v_add_f32_e32 v161, v161, v152
	v_cvt_pk_f16_f32 v180, v22, v23
	v_cvt_pk_f16_f32 v181, v24, v25
	v_mul_f32_e32 v150, v27, v27
	v_mul_f32_e32 v151, v29, v29
	v_fmac_f32_e32 v150, v26, v26
	v_fmac_f32_e32 v151, v28, v28
	v_add_f32_e32 v152, v150, v151
	v_add_f32_e32 v161, v161, v152
	v_cvt_pk_f16_f32 v182, v26, v27
	v_cvt_pk_f16_f32 v183, v28, v29
	v_mul_f32_e32 v150, v31, v31
	v_mul_f32_e32 v151, v33, v33
	v_fmac_f32_e32 v150, v30, v30
	v_fmac_f32_e32 v151, v32, v32
	v_add_f32_e32 v152, v150, v151
	v_add_f32_e32 v161, v161, v152
	v_cvt_pk_f16_f32 v184, v30, v31
	v_cvt_pk_f16_f32 v185, v32, v33
	global_store_dwordx2 v145, v[178:179], s[10:11]
	global_store_dwordx2 v145, v[180:181], s[10:11] offset:512
	global_store_dwordx2 v145, v[182:183], s[10:11] offset:1024
	global_store_dwordx2 v145, v[184:185], s[10:11] offset:1536
	v_mul_f32_e32 v150, v35, v35
	v_mul_f32_e32 v151, v37, v37
	v_fmac_f32_e32 v150, v34, v34
; __device__ void p0_xconv(const Args& a) {
;     ...
;         for (int r = 0; r < 4; ++r) {
;             const int row = row0 + r * nwv;
;             if (row < MROWS) {
;                 float ss = 0.f;
; #pragma unroll
;                 for (int i = 0; i < 4; ++i) {
;                     const f32x4 x = v[r][i];
;                     ss += (x[0] * x[0] + x[1] * x[1]) + (x[2] * x[2] + x[3] * x[3]);
;                     f16x4 h; h[0] = (f16)x[0]; h[1] = (f16)x[1]; h[2] = (f16)x[2]; h[3] = (f16)x[3];
;                     *(f16x4*)(XH + (size_t)row * DM + i * 256 + lane * 4) = h;
;                 }
; #pragma unroll
;                 for (int o = 1; o < 64; o <<= 1) ss += __shfl_xor(ss, o);
;                 if (lane < 16) SS[(size_t)row * 16 + lane] = (lane == 0) ? ss : 0.f;
	v_fmac_f32_e32 v151, v36, v36
	v_add_f32_e32 v162, v150, v151
	v_cvt_pk_f16_f32 v170, v34, v35
	v_cvt_pk_f16_f32 v171, v36, v37
	v_mul_f32_e32 v150, v39, v39
	v_mul_f32_e32 v151, v41, v41
	v_fmac_f32_e32 v150, v38, v38
	v_fmac_f32_e32 v151, v40, v40
	v_add_f32_e32 v152, v150, v151
	v_add_f32_e32 v162, v162, v152
	v_cvt_pk_f16_f32 v172, v38, v39
	v_cvt_pk_f16_f32 v173, v40, v41
	v_mul_f32_e32 v150, v43, v43
	v_mul_f32_e32 v151, v45, v45
	v_fmac_f32_e32 v150, v42, v42
	v_fmac_f32_e32 v151, v44, v44
	v_add_f32_e32 v152, v150, v151
	v_add_f32_e32 v162, v162, v152
	v_cvt_pk_f16_f32 v174, v42, v43
	v_cvt_pk_f16_f32 v175, v44, v45
	v_mul_f32_e32 v150, v47, v47
	v_mul_f32_e32 v151, v49, v49
	v_fmac_f32_e32 v150, v46, v46
	v_fmac_f32_e32 v151, v48, v48
	v_add_f32_e32 v152, v150, v151
	v_add_f32_e32 v162, v162, v152
	v_cvt_pk_f16_f32 v176, v46, v47
	v_cvt_pk_f16_f32 v177, v48, v49
	global_store_dwordx2 v146, v[170:171], s[10:11]
	global_store_dwordx2 v146, v[172:173], s[10:11] offset:512
	global_store_dwordx2 v146, v[174:175], s[10:11] offset:1024
	global_store_dwordx2 v146, v[176:177], s[10:11] offset:1536
	v_mul_f32_e32 v150, v51, v51
	v_mul_f32_e32 v151, v53, v53
	v_fmac_f32_e32 v150, v50, v50
	v_fmac_f32_e32 v151, v52, v52
	v_add_f32_e32 v163, v150, v151
	v_cvt_pk_f16_f32 v178, v50, v51
	v_cvt_pk_f16_f32 v179, v52, v53
	v_mul_f32_e32 v150, v55, v55
	v_mul_f32_e32 v151, v57, v57
	v_fmac_f32_e32 v150, v54, v54
	v_fmac_f32_e32 v151, v56, v56
	v_add_f32_e32 v152, v150, v151
	v_add_f32_e32 v163, v163, v152
	v_cvt_pk_f16_f32 v180, v54, v55
	v_cvt_pk_f16_f32 v181, v56, v57
	v_mul_f32_e32 v150, v59, v59
	v_mul_f32_e32 v151, v61, v61
	v_fmac_f32_e32 v150, v58, v58
	v_fmac_f32_e32 v151, v60, v60
	v_add_f32_e32 v152, v150, v151
	v_add_f32_e32 v163, v163, v152
	v_cvt_pk_f16_f32 v182, v58, v59
	v_cvt_pk_f16_f32 v183, v60, v61
	v_mul_f32_e32 v150, v63, v63
	v_mul_f32_e32 v151, v65, v65
	v_fmac_f32_e32 v150, v62, v62
	v_fmac_f32_e32 v151, v64, v64
	v_add_f32_e32 v152, v150, v151
	v_add_f32_e32 v163, v163, v152
	v_cvt_pk_f16_f32 v184, v62, v63
	v_cvt_pk_f16_f32 v185, v64, v65
	global_store_dwordx2 v147, v[178:179], s[10:11]
	global_store_dwordx2 v147, v[180:181], s[10:11] offset:512
	global_store_dwordx2 v147, v[182:183], s[10:11] offset:1024
	global_store_dwordx2 v147, v[184:185], s[10:11] offset:1536
	ds_bpermute_b32 v164, v130, v160
	ds_bpermute_b32 v165, v130, v161
	ds_bpermute_b32 v166, v130, v162
	ds_bpermute_b32 v167, v130, v163
	s_waitcnt lgkmcnt(0)
	v_add_f32_e32 v160, v160, v164
	v_add_f32_e32 v161, v161, v165
	v_add_f32_e32 v162, v162, v166
	v_add_f32_e32 v163, v163, v167
	ds_bpermute_b32 v164, v131, v160
	ds_bpermute_b32 v165, v131, v161
	ds_bpermute_b32 v166, v131, v162
	ds_bpermute_b32 v167, v131, v163
	s_waitcnt lgkmcnt(0)
	v_add_f32_e32 v160, v160, v164
	v_add_f32_e32 v161, v161, v165
	v_add_f32_e32 v162, v162, v166
	v_add_f32_e32 v163, v163, v167
	ds_bpermute_b32 v164, v132, v160
	ds_bpermute_b32 v165, v132, v161
	ds_bpermute_b32 v166, v132, v162
	ds_bpermute_b32 v167, v132, v163
	s_waitcnt lgkmcnt(0)
	v_add_f32_e32 v160, v160, v164
	v_add_f32_e32 v161, v161, v165
	v_add_f32_e32 v162, v162, v166
	v_add_f32_e32 v163, v163, v167
	ds_bpermute_b32 v164, v133, v160
	ds_bpermute_b32 v165, v133, v161
	ds_bpermute_b32 v166, v133, v162
	ds_bpermute_b32 v167, v133, v163
	s_waitcnt lgkmcnt(0)
	v_add_f32_e32 v160, v160, v164
	v_add_f32_e32 v161, v161, v165
	v_add_f32_e32 v162, v162, v166
	v_add_f32_e32 v163, v163, v167
	ds_bpermute_b32 v164, v134, v160
	ds_bpermute_b32 v165, v134, v161
	ds_bpermute_b32 v166, v134, v162
	ds_bpermute_b32 v167, v134, v163
	s_waitcnt lgkmcnt(0)
	v_add_f32_e32 v160, v160, v164
	v_add_f32_e32 v161, v161, v165
	v_add_f32_e32 v162, v162, v166
	v_add_f32_e32 v163, v163, v167
	ds_bpermute_b32 v164, v135, v160
	ds_bpermute_b32 v165, v135, v161
	ds_bpermute_b32 v166, v135, v162
	ds_bpermute_b32 v167, v135, v163
	s_waitcnt lgkmcnt(0)
	v_add_f32_e32 v160, v160, v164
	v_add_f32_e32 v161, v161, v165
	v_add_f32_e32 v162, v162, v166
	v_add_f32_e32 v163, v163, v167
	v_cndmask_b32_e64 v164, 0, v160, s[12:13]
	v_cndmask_b32_e64 v165, 0, v161, s[12:13]
	v_cndmask_b32_e64 v166, 0, v162, s[12:13]
	v_cndmask_b32_e64 v167, 0, v163, s[12:13]
	s_mov_b64 exec, 0xffff
	global_store_dword v186, v164, s[6:7]
	global_store_dword v187, v165, s[6:7]
	global_store_dword v188, v166, s[6:7]
	global_store_dword v189, v167, s[6:7]
	s_mov_b64 exec, -1
	s_add_i32 s6, s3, 0x6000
	s_lshl_b32 s6, s6, 12
	s_add_u32 s4, s18, s6
	s_addc_u32 s5, s19, 0
	global_load_dwordx4 v[2:5], v140, s[4:5] nt
	global_load_dwordx4 v[6:9], v140, s[4:5] offset:1024 nt
	global_load_dwordx4 v[10:13], v140, s[4:5] offset:2048 nt
	global_load_dwordx4 v[14:17], v140, s[4:5] offset:3072 nt
	global_load_dwordx4 v[18:21], v141, s[4:5] nt
	global_load_dwordx4 v[22:25], v141, s[4:5] offset:1024 nt
	global_load_dwordx4 v[26:29], v141, s[4:5] offset:2048 nt
	global_load_dwordx4 v[30:33], v141, s[4:5] offset:3072 nt
	global_load_dwordx4 v[34:37], v142, s[4:5] nt
	global_load_dwordx4 v[38:41], v142, s[4:5] offset:1024 nt
	global_load_dwordx4 v[42:45], v142, s[4:5] offset:2048 nt
	global_load_dwordx4 v[46:49], v142, s[4:5] offset:3072 nt
	global_load_dwordx4 v[50:53], v143, s[4:5] nt
	global_load_dwordx4 v[54:57], v143, s[4:5] offset:1024 nt
	global_load_dwordx4 v[58:61], v143, s[4:5] offset:2048 nt
	global_load_dwordx4 v[62:65], v143, s[4:5] offset:3072 nt
	s_waitcnt vmcnt(36)
; __device__ void p0_xconv(const Args& a) {
;     ...
; #pragma unroll
;         for (int r = 0; r < 4; ++r) {
;             const int row = row0 + r * nwv;
;             if (row < MROWS) {
;                 float ss = 0.f;
; #pragma unroll
;                 for (int i = 0; i < 4; ++i) {
;                     const f32x4 x = v[r][i];
;                     ss += (x[0] * x[0] + x[1] * x[1]) + (x[2] * x[2] + x[3] * x[3]);
;                     f16x4 h; h[0] = (f16)x[0]; h[1] = (f16)x[1]; h[2] = (f16)x[2]; h[3] = (f16)x[3];
;                     *(f16x4*)(XH + (size_t)row * DM + i * 256 + lane * 4) = h;
;                 }
; #pragma unroll
;                 for (int o = 1; o < 64; o <<= 1) ss += __shfl_xor(ss, o);
;                 if (lane < 16) SS[(size_t)row * 16 + lane] = (lane == 0) ? ss : 0.f;
;             }
	s_add_i32 s6, s3, 0x9000
	s_lshl_b32 s7, s6, 11
	s_add_u32 s10, s40, s7
	s_addc_u32 s11, s41, 0
	s_lshl_b32 s7, s6, 6
	s_add_u32 s6, s40, s7
	s_addc_u32 s7, s41, 0
	s_add_u32 s6, s6, 0x1f800000
	s_addc_u32 s7, s7, 0
	v_mul_f32_e32 v150, v67, v67
	v_mul_f32_e32 v151, v69, v69
	v_fmac_f32_e32 v150, v66, v66
	v_fmac_f32_e32 v151, v68, v68
	v_add_f32_e32 v160, v150, v151
	v_cvt_pk_f16_f32 v170, v66, v67
	v_cvt_pk_f16_f32 v171, v68, v69
	v_mul_f32_e32 v150, v71, v71
	v_mul_f32_e32 v151, v73, v73
	v_fmac_f32_e32 v150, v70, v70
	v_fmac_f32_e32 v151, v72, v72
	v_add_f32_e32 v152, v150, v151
	v_add_f32_e32 v160, v160, v152
	v_cvt_pk_f16_f32 v172, v70, v71
	v_cvt_pk_f16_f32 v173, v72, v73
	v_mul_f32_e32 v150, v75, v75
	v_mul_f32_e32 v151, v77, v77
	v_fmac_f32_e32 v150, v74, v74
	v_fmac_f32_e32 v151, v76, v76
	v_add_f32_e32 v152, v150, v151
	v_add_f32_e32 v160, v160, v152
	v_cvt_pk_f16_f32 v174, v74, v75
	v_cvt_pk_f16_f32 v175, v76, v77
	v_mul_f32_e32 v150, v79, v79
	v_mul_f32_e32 v151, v81, v81
	v_fmac_f32_e32 v150, v78, v78
	v_fmac_f32_e32 v151, v80, v80
	v_add_f32_e32 v152, v150, v151
	v_add_f32_e32 v160, v160, v152
	v_cvt_pk_f16_f32 v176, v78, v79
	v_cvt_pk_f16_f32 v177, v80, v81
	global_store_dwordx2 v144, v[170:171], s[10:11]
	global_store_dwordx2 v144, v[172:173], s[10:11] offset:512
	global_store_dwordx2 v144, v[174:175], s[10:11] offset:1024
	global_store_dwordx2 v144, v[176:177], s[10:11] offset:1536
	v_mul_f32_e32 v150, v83, v83
	v_mul_f32_e32 v151, v85, v85
	v_fmac_f32_e32 v150, v82, v82
	v_fmac_f32_e32 v151, v84, v84
	v_add_f32_e32 v161, v150, v151
	v_cvt_pk_f16_f32 v178, v82, v83
	v_cvt_pk_f16_f32 v179, v84, v85
	v_mul_f32_e32 v150, v87, v87
	v_mul_f32_e32 v151, v89, v89
	v_fmac_f32_e32 v150, v86, v86
	v_fmac_f32_e32 v151, v88, v88
	v_add_f32_e32 v152, v150, v151
	v_add_f32_e32 v161, v161, v152
	v_cvt_pk_f16_f32 v180, v86, v87
	v_cvt_pk_f16_f32 v181, v88, v89
	v_mul_f32_e32 v150, v91, v91
	v_mul_f32_e32 v151, v93, v93
	v_fmac_f32_e32 v150, v90, v90
	v_fmac_f32_e32 v151, v92, v92
	v_add_f32_e32 v152, v150, v151
	v_add_f32_e32 v161, v161, v152
	v_cvt_pk_f16_f32 v182, v90, v91
	v_cvt_pk_f16_f32 v183, v92, v93
	v_mul_f32_e32 v150, v95, v95
	v_mul_f32_e32 v151, v97, v97
	v_fmac_f32_e32 v150, v94, v94
	v_fmac_f32_e32 v151, v96, v96
	v_add_f32_e32 v152, v150, v151
	v_add_f32_e32 v161, v161, v152
	v_cvt_pk_f16_f32 v184, v94, v95
	v_cvt_pk_f16_f32 v185, v96, v97
	global_store_dwordx2 v145, v[178:179], s[10:11]
	global_store_dwordx2 v145, v[180:181], s[10:11] offset:512
	global_store_dwordx2 v145, v[182:183], s[10:11] offset:1024
	global_store_dwordx2 v145, v[184:185], s[10:11] offset:1536
	v_mul_f32_e32 v150, v99, v99
	v_mul_f32_e32 v151, v101, v101
	v_fmac_f32_e32 v150, v98, v98
	v_fmac_f32_e32 v151, v100, v100
	v_add_f32_e32 v162, v150, v151
	v_cvt_pk_f16_f32 v170, v98, v99
	v_cvt_pk_f16_f32 v171, v100, v101
	v_mul_f32_e32 v150, v103, v103
	v_mul_f32_e32 v151, v105, v105
	v_fmac_f32_e32 v150, v102, v102
	v_fmac_f32_e32 v151, v104, v104
	v_add_f32_e32 v152, v150, v151
	v_add_f32_e32 v162, v162, v152
	v_cvt_pk_f16_f32 v172, v102, v103
	v_cvt_pk_f16_f32 v173, v104, v105
	v_mul_f32_e32 v150, v107, v107
	v_mul_f32_e32 v151, v109, v109
	v_fmac_f32_e32 v150, v106, v106
	v_fmac_f32_e32 v151, v108, v108
	v_add_f32_e32 v152, v150, v151
	v_add_f32_e32 v162, v162, v152
	v_cvt_pk_f16_f32 v174, v106, v107
	v_cvt_pk_f16_f32 v175, v108, v109
	v_mul_f32_e32 v150, v111, v111
	v_mul_f32_e32 v151, v113, v113
	v_fmac_f32_e32 v150, v110, v110
	v_fmac_f32_e32 v151, v112, v112
	v_add_f32_e32 v152, v150, v151
	v_add_f32_e32 v162, v162, v152
	v_cvt_pk_f16_f32 v176, v110, v111
	v_cvt_pk_f16_f32 v177, v112, v113
	global_store_dwordx2 v146, v[170:171], s[10:11]
	global_store_dwordx2 v146, v[172:173], s[10:11] offset:512
	global_store_dwordx2 v146, v[174:175], s[10:11] offset:1024
	global_store_dwordx2 v146, v[176:177], s[10:11] offset:1536
	v_mul_f32_e32 v150, v115, v115
	v_mul_f32_e32 v151, v117, v117
	v_fmac_f32_e32 v150, v114, v114
	v_fmac_f32_e32 v151, v116, v116
	v_add_f32_e32 v163, v150, v151
	v_cvt_pk_f16_f32 v178, v114, v115
	v_cvt_pk_f16_f32 v179, v116, v117
	v_mul_f32_e32 v150, v119, v119
	v_mul_f32_e32 v151, v121, v121
	v_fmac_f32_e32 v150, v118, v118
	v_fmac_f32_e32 v151, v120, v120
	v_add_f32_e32 v152, v150, v151
	v_add_f32_e32 v163, v163, v152
	v_cvt_pk_f16_f32 v180, v118, v119
	v_cvt_pk_f16_f32 v181, v120, v121
	v_mul_f32_e32 v150, v123, v123
	v_mul_f32_e32 v151, v125, v125
	v_fmac_f32_e32 v150, v122, v122
	v_fmac_f32_e32 v151, v124, v124
	v_add_f32_e32 v152, v150, v151
	v_add_f32_e32 v163, v163, v152
	v_cvt_pk_f16_f32 v182, v122, v123
	v_cvt_pk_f16_f32 v183, v124, v125
	v_mul_f32_e32 v150, v127, v127
	v_mul_f32_e32 v151, v129, v129
	v_fmac_f32_e32 v150, v126, v126
	v_fmac_f32_e32 v151, v128, v128
	v_add_f32_e32 v152, v150, v151
	v_add_f32_e32 v163, v163, v152
	v_cvt_pk_f16_f32 v184, v126, v127
	v_cvt_pk_f16_f32 v185, v128, v129
	global_store_dwordx2 v147, v[178:179], s[10:11]
	global_store_dwordx2 v147, v[180:181], s[10:11] offset:512
	global_store_dwordx2 v147, v[182:183], s[10:11] offset:1024
	global_store_dwordx2 v147, v[184:185], s[10:11] offset:1536
	ds_bpermute_b32 v164, v130, v160
	ds_bpermute_b32 v165, v130, v161
	ds_bpermute_b32 v166, v130, v162
	ds_bpermute_b32 v167, v130, v163
	s_waitcnt lgkmcnt(0)
	v_add_f32_e32 v160, v160, v164
	v_add_f32_e32 v161, v161, v165
	v_add_f32_e32 v162, v162, v166
	v_add_f32_e32 v163, v163, v167
	ds_bpermute_b32 v164, v131, v160
	ds_bpermute_b32 v165, v131, v161
	ds_bpermute_b32 v166, v131, v162
	ds_bpermute_b32 v167, v131, v163
	s_waitcnt lgkmcnt(0)
; __device__ void p0_xconv(const Args& a) {
;     ...
;     for (int row0 = (int)blockIdx.x * 8 + wv; row0 < MROWS; row0 += 4 * nwv) {
;         f32x4 v[4][4];
; #pragma unroll
;         for (int r = 0; r < 4; ++r) {
;             const int row = row0 + r * nwv;
;             if (row < MROWS) {
;                 const float* src = (row < ROWS_PROMPT) ? a.x_prompt + (size_t)row * DM : a.x_sample + (size_t)(row - ROWS_PROMPT) * DM;
; #pragma unroll
;                 for (int i = 0; i < 4; ++i) v[r][i] = __builtin_nontemporal_load((const f32x4*)(src + i * 256 + lane * 4));
;             }
;         }
; #pragma unroll
;         for (int r = 0; r < 4; ++r) {
;             const int row = row0 + r * nwv;
;             if (row < MROWS) {
;                 float ss = 0.f;
; #pragma unroll
;                 for (int i = 0; i < 4; ++i) {
;                     const f32x4 x = v[r][i];
;                     ss += (x[0] * x[0] + x[1] * x[1]) + (x[2] * x[2] + x[3] * x[3]);
;                     f16x4 h; h[0] = (f16)x[0]; h[1] = (f16)x[1]; h[2] = (f16)x[2]; h[3] = (f16)x[3];
;                     *(f16x4*)(XH + (size_t)row * DM + i * 256 + lane * 4) = h;
;                 }
; #pragma unroll
;                 for (int o = 1; o < 64; o <<= 1) ss += __shfl_xor(ss, o);
;                 if (lane < 16) SS[(size_t)row * 16 + lane] = (lane == 0) ? ss : 0.f;
;             }
	v_add_f32_e32 v160, v160, v164
	v_add_f32_e32 v161, v161, v165
	v_add_f32_e32 v162, v162, v166
	v_add_f32_e32 v163, v163, v167
	ds_bpermute_b32 v164, v132, v160
	ds_bpermute_b32 v165, v132, v161
	ds_bpermute_b32 v166, v132, v162
	ds_bpermute_b32 v167, v132, v163
	s_waitcnt lgkmcnt(0)
	v_add_f32_e32 v160, v160, v164
	v_add_f32_e32 v161, v161, v165
	v_add_f32_e32 v162, v162, v166
	v_add_f32_e32 v163, v163, v167
	ds_bpermute_b32 v164, v133, v160
	ds_bpermute_b32 v165, v133, v161
	ds_bpermute_b32 v166, v133, v162
	ds_bpermute_b32 v167, v133, v163
	s_waitcnt lgkmcnt(0)
	v_add_f32_e32 v160, v160, v164
	v_add_f32_e32 v161, v161, v165
	v_add_f32_e32 v162, v162, v166
	v_add_f32_e32 v163, v163, v167
	ds_bpermute_b32 v164, v134, v160
	ds_bpermute_b32 v165, v134, v161
	ds_bpermute_b32 v166, v134, v162
	ds_bpermute_b32 v167, v134, v163
	s_waitcnt lgkmcnt(0)
	v_add_f32_e32 v160, v160, v164
	v_add_f32_e32 v161, v161, v165
	v_add_f32_e32 v162, v162, v166
	v_add_f32_e32 v163, v163, v167
	ds_bpermute_b32 v164, v135, v160
	ds_bpermute_b32 v165, v135, v161
	ds_bpermute_b32 v166, v135, v162
	ds_bpermute_b32 v167, v135, v163
	s_waitcnt lgkmcnt(0)
	v_add_f32_e32 v160, v160, v164
	v_add_f32_e32 v161, v161, v165
	v_add_f32_e32 v162, v162, v166
	v_add_f32_e32 v163, v163, v167
	v_cndmask_b32_e64 v164, 0, v160, s[12:13]
	v_cndmask_b32_e64 v165, 0, v161, s[12:13]
	v_cndmask_b32_e64 v166, 0, v162, s[12:13]
	v_cndmask_b32_e64 v167, 0, v163, s[12:13]
	s_mov_b64 exec, 0xffff
	global_store_dword v186, v164, s[6:7]
	global_store_dword v187, v165, s[6:7]
	global_store_dword v188, v166, s[6:7]
	global_store_dword v189, v167, s[6:7]
	s_mov_b64 exec, -1
	s_add_i32 s6, s3, 0x7000
	s_lshl_b32 s6, s6, 12
	s_add_u32 s4, s18, s6
	s_addc_u32 s5, s19, 0
	global_load_dwordx4 v[66:69], v140, s[4:5] nt
	global_load_dwordx4 v[70:73], v140, s[4:5] offset:1024 nt
	global_load_dwordx4 v[74:77], v140, s[4:5] offset:2048 nt
	global_load_dwordx4 v[78:81], v140, s[4:5] offset:3072 nt
	global_load_dwordx4 v[82:85], v141, s[4:5] nt
	global_load_dwordx4 v[86:89], v141, s[4:5] offset:1024 nt
	global_load_dwordx4 v[90:93], v141, s[4:5] offset:2048 nt
	global_load_dwordx4 v[94:97], v141, s[4:5] offset:3072 nt
	global_load_dwordx4 v[98:101], v142, s[4:5] nt
	global_load_dwordx4 v[102:105], v142, s[4:5] offset:1024 nt
	global_load_dwordx4 v[106:109], v142, s[4:5] offset:2048 nt
	global_load_dwordx4 v[110:113], v142, s[4:5] offset:3072 nt
	global_load_dwordx4 v[114:117], v143, s[4:5] nt
	global_load_dwordx4 v[118:121], v143, s[4:5] offset:1024 nt
	global_load_dwordx4 v[122:125], v143, s[4:5] offset:2048 nt
	global_load_dwordx4 v[126:129], v143, s[4:5] offset:3072 nt
	s_waitcnt vmcnt(36)
	s_add_i32 s6, s3, 0xa000
	s_lshl_b32 s7, s6, 11
	s_add_u32 s10, s40, s7
	s_addc_u32 s11, s41, 0
	s_lshl_b32 s7, s6, 6
	s_add_u32 s6, s40, s7
	s_addc_u32 s7, s41, 0
	s_add_u32 s6, s6, 0x1f800000
	s_addc_u32 s7, s7, 0
	v_mul_f32_e32 v150, v3, v3
	v_mul_f32_e32 v151, v5, v5
	v_fmac_f32_e32 v150, v2, v2
	v_fmac_f32_e32 v151, v4, v4
	v_add_f32_e32 v160, v150, v151
	v_cvt_pk_f16_f32 v170, v2, v3
	v_cvt_pk_f16_f32 v171, v4, v5
	v_mul_f32_e32 v150, v7, v7
	v_mul_f32_e32 v151, v9, v9
	v_fmac_f32_e32 v150, v6, v6
	v_fmac_f32_e32 v151, v8, v8
	v_add_f32_e32 v152, v150, v151
	v_add_f32_e32 v160, v160, v152
	v_cvt_pk_f16_f32 v172, v6, v7
	v_cvt_pk_f16_f32 v173, v8, v9
	v_mul_f32_e32 v150, v11, v11
	v_mul_f32_e32 v151, v13, v13
	v_fmac_f32_e32 v150, v10, v10
	v_fmac_f32_e32 v151, v12, v12
	v_add_f32_e32 v152, v150, v151
	v_add_f32_e32 v160, v160, v152
	v_cvt_pk_f16_f32 v174, v10, v11
	v_cvt_pk_f16_f32 v175, v12, v13
	v_mul_f32_e32 v150, v15, v15
	v_mul_f32_e32 v151, v17, v17
	v_fmac_f32_e32 v150, v14, v14
	v_fmac_f32_e32 v151, v16, v16
	v_add_f32_e32 v152, v150, v151
	v_add_f32_e32 v160, v160, v152
	v_cvt_pk_f16_f32 v176, v14, v15
	v_cvt_pk_f16_f32 v177, v16, v17
	global_store_dwordx2 v144, v[170:171], s[10:11]
	global_store_dwordx2 v144, v[172:173], s[10:11] offset:512
	global_store_dwordx2 v144, v[174:175], s[10:11] offset:1024
	global_store_dwordx2 v144, v[176:177], s[10:11] offset:1536
	v_mul_f32_e32 v150, v19, v19
	v_mul_f32_e32 v151, v21, v21
	v_fmac_f32_e32 v150, v18, v18
	v_fmac_f32_e32 v151, v20, v20
	v_add_f32_e32 v161, v150, v151
	v_cvt_pk_f16_f32 v178, v18, v19
	v_cvt_pk_f16_f32 v179, v20, v21
	v_mul_f32_e32 v150, v23, v23
	v_mul_f32_e32 v151, v25, v25
	v_fmac_f32_e32 v150, v22, v22
	v_fmac_f32_e32 v151, v24, v24
	v_add_f32_e32 v152, v150, v151
	v_add_f32_e32 v161, v161, v152
	v_cvt_pk_f16_f32 v180, v22, v23
	v_cvt_pk_f16_f32 v181, v24, v25
	v_mul_f32_e32 v150, v27, v27
	v_mul_f32_e32 v151, v29, v29
	v_fmac_f32_e32 v150, v26, v26
	v_fmac_f32_e32 v151, v28, v28
	v_add_f32_e32 v152, v150, v151
	v_add_f32_e32 v161, v161, v152
	v_cvt_pk_f16_f32 v182, v26, v27
	v_cvt_pk_f16_f32 v183, v28, v29
	v_mul_f32_e32 v150, v31, v31
	v_mul_f32_e32 v151, v33, v33
	v_fmac_f32_e32 v150, v30, v30
	v_fmac_f32_e32 v151, v32, v32
	v_add_f32_e32 v152, v150, v151
	v_add_f32_e32 v161, v161, v152
	v_cvt_pk_f16_f32 v184, v30, v31
	v_cvt_pk_f16_f32 v185, v32, v33
	global_store_dwordx2 v145, v[178:179], s[10:11]
	global_store_dwordx2 v145, v[180:181], s[10:11] offset:512
	global_store_dwordx2 v145, v[182:183], s[10:11] offset:1024
	global_store_dwordx2 v145, v[184:185], s[10:11] offset:1536
	v_mul_f32_e32 v150, v35, v35
	v_mul_f32_e32 v151, v37, v37
	v_fmac_f32_e32 v150, v34, v34
	v_fmac_f32_e32 v151, v36, v36
	v_add_f32_e32 v162, v150, v151
	v_cvt_pk_f16_f32 v170, v34, v35
	v_cvt_pk_f16_f32 v171, v36, v37
	v_mul_f32_e32 v150, v39, v39
	v_mul_f32_e32 v151, v41, v41
	v_fmac_f32_e32 v150, v38, v38
	v_fmac_f32_e32 v151, v40, v40
	v_add_f32_e32 v152, v150, v151
; __device__ void p0_xconv(const Args& a) {
;     ...
; #pragma unroll
;         for (int r = 0; r < 4; ++r) {
;             const int row = row0 + r * nwv;
;             if (row < MROWS) {
;                 float ss = 0.f;
; #pragma unroll
;                 for (int i = 0; i < 4; ++i) {
;                     const f32x4 x = v[r][i];
;                     ss += (x[0] * x[0] + x[1] * x[1]) + (x[2] * x[2] + x[3] * x[3]);
;                     f16x4 h; h[0] = (f16)x[0]; h[1] = (f16)x[1]; h[2] = (f16)x[2]; h[3] = (f16)x[3];
;                     *(f16x4*)(XH + (size_t)row * DM + i * 256 + lane * 4) = h;
;                 }
; #pragma unroll
;                 for (int o = 1; o < 64; o <<= 1) ss += __shfl_xor(ss, o);
;                 if (lane < 16) SS[(size_t)row * 16 + lane] = (lane == 0) ? ss : 0.f;
;             }
	v_add_f32_e32 v162, v162, v152
	v_cvt_pk_f16_f32 v172, v38, v39
	v_cvt_pk_f16_f32 v173, v40, v41
	v_mul_f32_e32 v150, v43, v43
	v_mul_f32_e32 v151, v45, v45
	v_fmac_f32_e32 v150, v42, v42
	v_fmac_f32_e32 v151, v44, v44
	v_add_f32_e32 v152, v150, v151
	v_add_f32_e32 v162, v162, v152
	v_cvt_pk_f16_f32 v174, v42, v43
	v_cvt_pk_f16_f32 v175, v44, v45
	v_mul_f32_e32 v150, v47, v47
	v_mul_f32_e32 v151, v49, v49
	v_fmac_f32_e32 v150, v46, v46
	v_fmac_f32_e32 v151, v48, v48
	v_add_f32_e32 v152, v150, v151
	v_add_f32_e32 v162, v162, v152
	v_cvt_pk_f16_f32 v176, v46, v47
	v_cvt_pk_f16_f32 v177, v48, v49
	global_store_dwordx2 v146, v[170:171], s[10:11]
	global_store_dwordx2 v146, v[172:173], s[10:11] offset:512
	global_store_dwordx2 v146, v[174:175], s[10:11] offset:1024
	global_store_dwordx2 v146, v[176:177], s[10:11] offset:1536
	v_mul_f32_e32 v150, v51, v51
	v_mul_f32_e32 v151, v53, v53
	v_fmac_f32_e32 v150, v50, v50
	v_fmac_f32_e32 v151, v52, v52
	v_add_f32_e32 v163, v150, v151
	v_cvt_pk_f16_f32 v178, v50, v51
	v_cvt_pk_f16_f32 v179, v52, v53
	v_mul_f32_e32 v150, v55, v55
	v_mul_f32_e32 v151, v57, v57
	v_fmac_f32_e32 v150, v54, v54
	v_fmac_f32_e32 v151, v56, v56
	v_add_f32_e32 v152, v150, v151
	v_add_f32_e32 v163, v163, v152
	v_cvt_pk_f16_f32 v180, v54, v55
	v_cvt_pk_f16_f32 v181, v56, v57
	v_mul_f32_e32 v150, v59, v59
	v_mul_f32_e32 v151, v61, v61
	v_fmac_f32_e32 v150, v58, v58
	v_fmac_f32_e32 v151, v60, v60
	v_add_f32_e32 v152, v150, v151
	v_add_f32_e32 v163, v163, v152
	v_cvt_pk_f16_f32 v182, v58, v59
	v_cvt_pk_f16_f32 v183, v60, v61
	v_mul_f32_e32 v150, v63, v63
	v_mul_f32_e32 v151, v65, v65
	v_fmac_f32_e32 v150, v62, v62
	v_fmac_f32_e32 v151, v64, v64
	v_add_f32_e32 v152, v150, v151
	v_add_f32_e32 v163, v163, v152
	v_cvt_pk_f16_f32 v184, v62, v63
	v_cvt_pk_f16_f32 v185, v64, v65
	global_store_dwordx2 v147, v[178:179], s[10:11]
	global_store_dwordx2 v147, v[180:181], s[10:11] offset:512
	global_store_dwordx2 v147, v[182:183], s[10:11] offset:1024
	global_store_dwordx2 v147, v[184:185], s[10:11] offset:1536
	ds_bpermute_b32 v164, v130, v160
	ds_bpermute_b32 v165, v130, v161
	ds_bpermute_b32 v166, v130, v162
	ds_bpermute_b32 v167, v130, v163
	s_waitcnt lgkmcnt(0)
	v_add_f32_e32 v160, v160, v164
	v_add_f32_e32 v161, v161, v165
	v_add_f32_e32 v162, v162, v166
	v_add_f32_e32 v163, v163, v167
	ds_bpermute_b32 v164, v131, v160
	ds_bpermute_b32 v165, v131, v161
	ds_bpermute_b32 v166, v131, v162
	ds_bpermute_b32 v167, v131, v163
	s_waitcnt lgkmcnt(0)
	v_add_f32_e32 v160, v160, v164
	v_add_f32_e32 v161, v161, v165
	v_add_f32_e32 v162, v162, v166
	v_add_f32_e32 v163, v163, v167
	ds_bpermute_b32 v164, v132, v160
	ds_bpermute_b32 v165, v132, v161
	ds_bpermute_b32 v166, v132, v162
	ds_bpermute_b32 v167, v132, v163
	s_waitcnt lgkmcnt(0)
	v_add_f32_e32 v160, v160, v164
	v_add_f32_e32 v161, v161, v165
	v_add_f32_e32 v162, v162, v166
	v_add_f32_e32 v163, v163, v167
	ds_bpermute_b32 v164, v133, v160
	ds_bpermute_b32 v165, v133, v161
	ds_bpermute_b32 v166, v133, v162
	ds_bpermute_b32 v167, v133, v163
	s_waitcnt lgkmcnt(0)
	v_add_f32_e32 v160, v160, v164
	v_add_f32_e32 v161, v161, v165
	v_add_f32_e32 v162, v162, v166
	v_add_f32_e32 v163, v163, v167
	ds_bpermute_b32 v164, v134, v160
	ds_bpermute_b32 v165, v134, v161
	ds_bpermute_b32 v166, v134, v162
	ds_bpermute_b32 v167, v134, v163
	s_waitcnt lgkmcnt(0)
	v_add_f32_e32 v160, v160, v164
	v_add_f32_e32 v161, v161, v165
	v_add_f32_e32 v162, v162, v166
	v_add_f32_e32 v163, v163, v167
	ds_bpermute_b32 v164, v135, v160
	ds_bpermute_b32 v165, v135, v161
	ds_bpermute_b32 v166, v135, v162
	ds_bpermute_b32 v167, v135, v163
	s_waitcnt lgkmcnt(0)
	v_add_f32_e32 v160, v160, v164
	v_add_f32_e32 v161, v161, v165
	v_add_f32_e32 v162, v162, v166
	v_add_f32_e32 v163, v163, v167
	v_cndmask_b32_e64 v164, 0, v160, s[12:13]
	v_cndmask_b32_e64 v165, 0, v161, s[12:13]
	v_cndmask_b32_e64 v166, 0, v162, s[12:13]
	v_cndmask_b32_e64 v167, 0, v163, s[12:13]
	s_mov_b64 exec, 0xffff
	global_store_dword v186, v164, s[6:7]
	global_store_dword v187, v165, s[6:7]
	global_store_dword v188, v166, s[6:7]
	global_store_dword v189, v167, s[6:7]
	s_mov_b64 exec, -1
	s_waitcnt vmcnt(20)
	s_add_i32 s6, s3, 0xb000
	s_lshl_b32 s7, s6, 11
	s_add_u32 s10, s40, s7
	s_addc_u32 s11, s41, 0
	s_lshl_b32 s7, s6, 6
	s_add_u32 s6, s40, s7
	s_addc_u32 s7, s41, 0
	s_add_u32 s6, s6, 0x1f800000
	s_addc_u32 s7, s7, 0
	v_mul_f32_e32 v150, v67, v67
	v_mul_f32_e32 v151, v69, v69
	v_fmac_f32_e32 v150, v66, v66
	v_fmac_f32_e32 v151, v68, v68
	v_add_f32_e32 v160, v150, v151
	v_cvt_pk_f16_f32 v170, v66, v67
	v_cvt_pk_f16_f32 v171, v68, v69
	v_mul_f32_e32 v150, v71, v71
	v_mul_f32_e32 v151, v73, v73
	v_fmac_f32_e32 v150, v70, v70
	v_fmac_f32_e32 v151, v72, v72
	v_add_f32_e32 v152, v150, v151
	v_add_f32_e32 v160, v160, v152
	v_cvt_pk_f16_f32 v172, v70, v71
	v_cvt_pk_f16_f32 v173, v72, v73
	v_mul_f32_e32 v150, v75, v75
	v_mul_f32_e32 v151, v77, v77
	v_fmac_f32_e32 v150, v74, v74
	v_fmac_f32_e32 v151, v76, v76
	v_add_f32_e32 v152, v150, v151
	v_add_f32_e32 v160, v160, v152
	v_cvt_pk_f16_f32 v174, v74, v75
	v_cvt_pk_f16_f32 v175, v76, v77
	v_mul_f32_e32 v150, v79, v79
	v_mul_f32_e32 v151, v81, v81
	v_fmac_f32_e32 v150, v78, v78
	v_fmac_f32_e32 v151, v80, v80
	v_add_f32_e32 v152, v150, v151
	v_add_f32_e32 v160, v160, v152
	v_cvt_pk_f16_f32 v176, v78, v79
	v_cvt_pk_f16_f32 v177, v80, v81
	global_store_dwordx2 v144, v[170:171], s[10:11]
	global_store_dwordx2 v144, v[172:173], s[10:11] offset:512
	global_store_dwordx2 v144, v[174:175], s[10:11] offset:1024
	global_store_dwordx2 v144, v[176:177], s[10:11] offset:1536
	v_mul_f32_e32 v150, v83, v83
	v_mul_f32_e32 v151, v85, v85
; __device__ void p0_xconv(const Args& a) {
;     ...
; #pragma unroll
;         for (int r = 0; r < 4; ++r) {
;             const int row = row0 + r * nwv;
;             if (row < MROWS) {
;                 float ss = 0.f;
; #pragma unroll
;                 for (int i = 0; i < 4; ++i) {
;                     const f32x4 x = v[r][i];
;                     ss += (x[0] * x[0] + x[1] * x[1]) + (x[2] * x[2] + x[3] * x[3]);
;                     f16x4 h; h[0] = (f16)x[0]; h[1] = (f16)x[1]; h[2] = (f16)x[2]; h[3] = (f16)x[3];
;                     *(f16x4*)(XH + (size_t)row * DM + i * 256 + lane * 4) = h;
;                 }
; #pragma unroll
;                 for (int o = 1; o < 64; o <<= 1) ss += __shfl_xor(ss, o);
;                 if (lane < 16) SS[(size_t)row * 16 + lane] = (lane == 0) ? ss : 0.f;
;             }
	v_fmac_f32_e32 v150, v82, v82
	v_fmac_f32_e32 v151, v84, v84
	v_add_f32_e32 v161, v150, v151
	v_cvt_pk_f16_f32 v178, v82, v83
	v_cvt_pk_f16_f32 v179, v84, v85
	v_mul_f32_e32 v150, v87, v87
	v_mul_f32_e32 v151, v89, v89
	v_fmac_f32_e32 v150, v86, v86
	v_fmac_f32_e32 v151, v88, v88
	v_add_f32_e32 v152, v150, v151
	v_add_f32_e32 v161, v161, v152
	v_cvt_pk_f16_f32 v180, v86, v87
	v_cvt_pk_f16_f32 v181, v88, v89
	v_mul_f32_e32 v150, v91, v91
	v_mul_f32_e32 v151, v93, v93
	v_fmac_f32_e32 v150, v90, v90
	v_fmac_f32_e32 v151, v92, v92
	v_add_f32_e32 v152, v150, v151
	v_add_f32_e32 v161, v161, v152
	v_cvt_pk_f16_f32 v182, v90, v91
	v_cvt_pk_f16_f32 v183, v92, v93
	v_mul_f32_e32 v150, v95, v95
	v_mul_f32_e32 v151, v97, v97
	v_fmac_f32_e32 v150, v94, v94
	v_fmac_f32_e32 v151, v96, v96
	v_add_f32_e32 v152, v150, v151
	v_add_f32_e32 v161, v161, v152
	v_cvt_pk_f16_f32 v184, v94, v95
	v_cvt_pk_f16_f32 v185, v96, v97
	global_store_dwordx2 v145, v[178:179], s[10:11]
	global_store_dwordx2 v145, v[180:181], s[10:11] offset:512
	global_store_dwordx2 v145, v[182:183], s[10:11] offset:1024
	global_store_dwordx2 v145, v[184:185], s[10:11] offset:1536
	v_mul_f32_e32 v150, v99, v99
	v_mul_f32_e32 v151, v101, v101
	v_fmac_f32_e32 v150, v98, v98
	v_fmac_f32_e32 v151, v100, v100
	v_add_f32_e32 v162, v150, v151
	v_cvt_pk_f16_f32 v170, v98, v99
	v_cvt_pk_f16_f32 v171, v100, v101
	v_mul_f32_e32 v150, v103, v103
	v_mul_f32_e32 v151, v105, v105
	v_fmac_f32_e32 v150, v102, v102
	v_fmac_f32_e32 v151, v104, v104
	v_add_f32_e32 v152, v150, v151
	v_add_f32_e32 v162, v162, v152
	v_cvt_pk_f16_f32 v172, v102, v103
	v_cvt_pk_f16_f32 v173, v104, v105
	v_mul_f32_e32 v150, v107, v107
	v_mul_f32_e32 v151, v109, v109
	v_fmac_f32_e32 v150, v106, v106
	v_fmac_f32_e32 v151, v108, v108
	v_add_f32_e32 v152, v150, v151
	v_add_f32_e32 v162, v162, v152
	v_cvt_pk_f16_f32 v174, v106, v107
	v_cvt_pk_f16_f32 v175, v108, v109
	v_mul_f32_e32 v150, v111, v111
	v_mul_f32_e32 v151, v113, v113
	v_fmac_f32_e32 v150, v110, v110
	v_fmac_f32_e32 v151, v112, v112
	v_add_f32_e32 v152, v150, v151
	v_add_f32_e32 v162, v162, v152
	v_cvt_pk_f16_f32 v176, v110, v111
	v_cvt_pk_f16_f32 v177, v112, v113
	global_store_dwordx2 v146, v[170:171], s[10:11]
	global_store_dwordx2 v146, v[172:173], s[10:11] offset:512
	global_store_dwordx2 v146, v[174:175], s[10:11] offset:1024
	global_store_dwordx2 v146, v[176:177], s[10:11] offset:1536
	v_mul_f32_e32 v150, v115, v115
	v_mul_f32_e32 v151, v117, v117
	v_fmac_f32_e32 v150, v114, v114
	v_fmac_f32_e32 v151, v116, v116
	v_add_f32_e32 v163, v150, v151
	v_cvt_pk_f16_f32 v178, v114, v115
	v_cvt_pk_f16_f32 v179, v116, v117
	v_mul_f32_e32 v150, v119, v119
	v_mul_f32_e32 v151, v121, v121
	v_fmac_f32_e32 v150, v118, v118
	v_fmac_f32_e32 v151, v120, v120
	v_add_f32_e32 v152, v150, v151
	v_add_f32_e32 v163, v163, v152
	v_cvt_pk_f16_f32 v180, v118, v119
	v_cvt_pk_f16_f32 v181, v120, v121
	v_mul_f32_e32 v150, v123, v123
	v_mul_f32_e32 v151, v125, v125
	v_fmac_f32_e32 v150, v122, v122
	v_fmac_f32_e32 v151, v124, v124
	v_add_f32_e32 v152, v150, v151
	v_add_f32_e32 v163, v163, v152
	v_cvt_pk_f16_f32 v182, v122, v123
	v_cvt_pk_f16_f32 v183, v124, v125
	v_mul_f32_e32 v150, v127, v127
	v_mul_f32_e32 v151, v129, v129
	v_fmac_f32_e32 v150, v126, v126
	v_fmac_f32_e32 v151, v128, v128
	v_add_f32_e32 v152, v150, v151
	v_add_f32_e32 v163, v163, v152
	v_cvt_pk_f16_f32 v184, v126, v127
	v_cvt_pk_f16_f32 v185, v128, v129
	global_store_dwordx2 v147, v[178:179], s[10:11]
	global_store_dwordx2 v147, v[180:181], s[10:11] offset:512
	global_store_dwordx2 v147, v[182:183], s[10:11] offset:1024
	global_store_dwordx2 v147, v[184:185], s[10:11] offset:1536
	ds_bpermute_b32 v164, v130, v160
	ds_bpermute_b32 v165, v130, v161
	ds_bpermute_b32 v166, v130, v162
	ds_bpermute_b32 v167, v130, v163
	s_waitcnt lgkmcnt(0)
	v_add_f32_e32 v160, v160, v164
	v_add_f32_e32 v161, v161, v165
	v_add_f32_e32 v162, v162, v166
	v_add_f32_e32 v163, v163, v167
	ds_bpermute_b32 v164, v131, v160
	ds_bpermute_b32 v165, v131, v161
	ds_bpermute_b32 v166, v131, v162
	ds_bpermute_b32 v167, v131, v163
	s_waitcnt lgkmcnt(0)
	v_add_f32_e32 v160, v160, v164
	v_add_f32_e32 v161, v161, v165
	v_add_f32_e32 v162, v162, v166
	v_add_f32_e32 v163, v163, v167
	ds_bpermute_b32 v164, v132, v160
	ds_bpermute_b32 v165, v132, v161
	ds_bpermute_b32 v166, v132, v162
	ds_bpermute_b32 v167, v132, v163
	s_waitcnt lgkmcnt(0)
	v_add_f32_e32 v160, v160, v164
	v_add_f32_e32 v161, v161, v165
	v_add_f32_e32 v162, v162, v166
	v_add_f32_e32 v163, v163, v167
	ds_bpermute_b32 v164, v133, v160
	ds_bpermute_b32 v165, v133, v161
	ds_bpermute_b32 v166, v133, v162
	ds_bpermute_b32 v167, v133, v163
	s_waitcnt lgkmcnt(0)
	v_add_f32_e32 v160, v160, v164
	v_add_f32_e32 v161, v161, v165
	v_add_f32_e32 v162, v162, v166
	v_add_f32_e32 v163, v163, v167
	ds_bpermute_b32 v164, v134, v160
	ds_bpermute_b32 v165, v134, v161
	ds_bpermute_b32 v166, v134, v162
	ds_bpermute_b32 v167, v134, v163
	s_waitcnt lgkmcnt(0)
	v_add_f32_e32 v160, v160, v164
	v_add_f32_e32 v161, v161, v165
	v_add_f32_e32 v162, v162, v166
	v_add_f32_e32 v163, v163, v167
	ds_bpermute_b32 v164, v135, v160
	ds_bpermute_b32 v165, v135, v161
	ds_bpermute_b32 v166, v135, v162
	ds_bpermute_b32 v167, v135, v163
	s_waitcnt lgkmcnt(0)
	v_add_f32_e32 v160, v160, v164
	v_add_f32_e32 v161, v161, v165
	v_add_f32_e32 v162, v162, v166
	v_add_f32_e32 v163, v163, v167
	v_cndmask_b32_e64 v164, 0, v160, s[12:13]
	v_cndmask_b32_e64 v165, 0, v161, s[12:13]
	v_cndmask_b32_e64 v166, 0, v162, s[12:13]
	v_cndmask_b32_e64 v167, 0, v163, s[12:13]
	s_mov_b64 exec, 0xffff
	global_store_dword v186, v164, s[6:7]
	global_store_dword v187, v165, s[6:7]
	global_store_dword v188, v166, s[6:7]
	global_store_dword v189, v167, s[6:7]
	s_mov_b64 exec, -1
	s_barrier
	s_branch .LBB0_112
; __device__ void p0_xconv(const Args& a) {
;     f16* XH = (f16*)(a.ws + WS_XH); float* SS = (float*)(a.ws + WS_SS);
;     int tid_ = threadIdx.x; asm volatile("" : "+v"(tid_));
;     const int lane = tid_ & 63, wv = tid_ >> 6;
;     const int nwv = (int)gridDim.x * 8;
;     for (int row0 = (int)blockIdx.x * 8 + wv; row0 < MROWS; row0 += 4 * nwv) {
;         f32x4 v[4][4];
; #pragma unroll
;         for (int r = 0; r < 4; ++r) {
;             const int row = row0 + r * nwv;
;             if (row < MROWS) {
;                 const float* src = (row < ROWS_PROMPT) ? a.x_prompt + (size_t)row * DM : a.x_sample + (size_t)(row - ROWS_PROMPT) * DM;
; #pragma unroll
;                 for (int i = 0; i < 4; ++i) v[r][i] = __builtin_nontemporal_load((const f32x4*)(src + i * 256 + lane * 4));
;             }
;         }
.LBB0_91:
	v_mov_b32_e32 v1, v0
	s_barrier
	s_mov_b32 s3, 0xc000
	v_ashrrev_i32_e32 v2, 6, v1
	v_lshl_add_u32 v78, s2, 3, v2
	v_add_u32_e32 v78, 0x6000, v78
	v_cmp_gt_i32_e32 vcc, s3, v78
	s_and_saveexec_b64 s[20:21], vcc
	s_cbranch_execz .LBB0_111
	v_and_b32_e32 v1, 63, v1
	v_mov_b32_e32 v67, 0
	v_lshlrev_b32_e32 v66, 2, v1
	v_lshlrev_b32_e32 v2, 3, v1
	v_mov_b32_e32 v3, v67
	s_load_dword s36, s[4:5], 0x0
	v_lshl_add_u64 v[68:69], s[40:41], 0, v[2:3]
	v_lshl_add_u64 v[2:3], s[40:41], 0, v[66:67]
	s_mov_b64 s[4:5], 0x1f800000
	v_cmp_gt_u32_e32 vcc, 16, v1
	v_lshl_add_u64 v[70:71], v[2:3], 0, s[4:5]
	v_cmp_eq_u32_e64 s[4:5], 0, v1
	v_mbcnt_lo_u32_b32 v1, -1, 0
	v_mbcnt_hi_u32_b32 v2, -1, v1
	v_and_b32_e32 v1, 64, v2
	v_add_u32_e32 v3, 64, v1
	v_xor_b32_e32 v1, 1, v2
	v_cmp_lt_i32_e64 s[6:7], v1, v3
	v_xor_b32_e32 v4, 2, v2
	s_waitcnt lgkmcnt(0)
	s_lshl_b32 s9, s36, 3
	v_cndmask_b32_e64 v1, v2, v1, s[6:7]
	v_cmp_lt_i32_e64 s[6:7], v4, v3
	s_add_i32 s44, s9, s9
	v_lshlrev_b32_e32 v1, 2, v1
	v_cndmask_b32_e64 v4, v2, v4, s[6:7]
	v_lshlrev_b32_e32 v80, 2, v4
	v_xor_b32_e32 v4, 4, v2
	v_cmp_lt_i32_e64 s[6:7], v4, v3
	s_lshl_b32 s33, s36, 4
	s_mul_i32 s36, s36, 24
	v_cndmask_b32_e64 v4, v2, v4, s[6:7]
	v_lshlrev_b32_e32 v81, 2, v4
	v_xor_b32_e32 v4, 8, v2
	v_cmp_lt_i32_e64 s[6:7], v4, v3
	s_mov_b64 s[22:23], 0
	s_movk_i32 s37, 0x4000
	v_cndmask_b32_e64 v4, v2, v4, s[6:7]
	v_lshlrev_b32_e32 v82, 2, v4
	v_xor_b32_e32 v4, 16, v2
	v_cmp_lt_i32_e64 s[6:7], v4, v3
	v_mov_b32_e32 v85, s19
	v_mov_b32_e32 v86, s17
	v_cndmask_b32_e64 v4, v2, v4, s[6:7]
	v_lshlrev_b32_e32 v83, 2, v4
	v_xor_b32_e32 v4, 32, v2
	v_cmp_lt_i32_e64 s[6:7], v4, v3
	v_mov_b32_e32 v87, s18
	v_mov_b32_e32 v88, s16
	v_cndmask_b32_e64 v2, v2, v4, s[6:7]
	v_lshlrev_b32_e32 v84, 2, v2
	v_lshlrev_b32_e32 v66, 2, v66
	s_add_i32 s44, s44, s9
	s_mov_b32 s45, 0xbfff
	s_branch .LBB0_94
